# attention context loop: loop-top vmcnt waits (which also drained the previous iteration's stores) hoisted to loop entry
# speedup vs baseline: 1.0022x; 1.0022x over previous
.LBB0_666:
	s_bfe_u32 s5, s83, 0x30005
	s_bfe_u32 s10, s83, 0x30002
	s_lshl_b32 s11, s5, 3
	s_and_b32 s4, s81, 0xff
	s_and_b32 s84, s82, 3
	s_or_b32 s85, s11, s10
	s_lshl_b32 s16, s4, 15
	s_lshl_b32 s58, s4, 17
	s_bfe_u32 s8, s81, 0x30005
	s_lshr_b32 s9, s83, 2
	s_lshl_b32 s50, s10, 7
	s_lshl_b32 s4, s84, 21
	s_and_b32 s6, s83, 0xff
	v_mov_b32_e32 v94, v1
	s_lshl_b32 s7, s83, 4
	s_lshl_b32 s11, s85, 15
	s_add_u32 s60, s63, s11
	v_ashrrev_i32_e32 v95, 31, v94
	s_addc_u32 s61, s64, 0
	v_lshlrev_b64 v[2:3], 4, v[94:95]
	s_add_u32 s86, s67, s11
	v_lshl_add_u64 v[26:27], s[60:61], 0, v[2:3]
	s_addc_u32 s87, s68, 0
	v_add_co_u32_e32 v10, vcc, s73, v26
	v_lshl_add_u64 v[30:31], s[86:87], 0, v[2:3]
	s_nop 0
	v_addc_co_u32_e32 v11, vcc, 0, v27, vcc
	v_add_co_u32_e32 v14, vcc, s73, v30
	global_load_dwordx4 v[2:5], v[26:27], off
	global_load_dwordx4 v[6:9], v[30:31], off
	v_addc_co_u32_e32 v15, vcc, 0, v31, vcc
	global_load_dwordx4 v[10:13], v[10:11], off
	s_nop 0
	global_load_dwordx4 v[14:17], v[14:15], off
	v_add_co_u32_e32 v18, vcc, s74, v26
	v_ashrrev_i32_e32 v110, 6, v94
	s_nop 0
	v_addc_co_u32_e32 v19, vcc, 0, v27, vcc
	v_add_co_u32_e32 v22, vcc, s74, v30
	global_load_dwordx4 v[18:21], v[18:19], off
	s_nop 0
	v_addc_co_u32_e32 v23, vcc, 0, v31, vcc
	v_add_co_u32_e32 v26, vcc, s75, v26
	global_load_dwordx4 v[22:25], v[22:23], off
	s_nop 0
	v_addc_co_u32_e32 v27, vcc, 0, v27, vcc
	global_load_dwordx4 v[26:29], v[26:27], off
	v_add_co_u32_e32 v30, vcc, s75, v30
	v_add_u32_e32 v34, 0x200, v94
	s_nop 0
	v_addc_co_u32_e32 v31, vcc, 0, v31, vcc
	global_load_dwordx4 v[30:33], v[30:31], off
	v_lshlrev_b32_e32 v35, 1, v94
	v_lshrrev_b32_e32 v38, 4, v94
	v_and_b32_e32 v40, 0xfffff00, v94
	v_lshlrev_b32_e32 v41, 4, v110
	v_and_b32_e32 v42, 0xc0, v35
	v_and_b32_e32 v35, 62, v35
	v_lshlrev_b32_e32 v43, 1, v34
	v_and_b32_e32 v95, 15, v94
	v_and_b32_e32 v38, 8, v38
	v_and_b32_e32 v34, 0xfffff00, v34
	v_and_b32_e32 v126, 48, v41
	v_or3_b32 v35, v40, v35, v42
	v_and_b32_e32 v40, 62, v43
	v_add_u32_e32 v38, 0, v38
	v_or_b32_e32 v113, v126, v95
	v_or3_b32 v34, v34, v40, v42
	v_add_u32_e32 v36, 0x400, v94
	v_lshl_add_u32 v39, v94, 4, 0
	v_lshl_add_u32 v35, v35, 4, v38
	v_lshlrev_b32_e32 v40, 11, v113
	v_lshl_add_u32 v34, v34, 4, v38
	v_add_u32_e32 v41, 0x8000, v35
	v_lshl_or_b32 v88, s5, 23, v40
	v_add_u32_e32 v40, 0x8000, v34
	v_add_u32_e32 v37, 0x600, v94
	s_mov_b32 s51, s17
	v_lshl_add_u64 v[34:35], s[38:39], 0, v[88:89]
	s_and_b32 s11, s7, 48
	v_ashrrev_i32_e32 v96, 8, v94
	v_lshl_add_u64 v[34:35], v[34:35], 0, s[50:51]
	v_and_b32_e32 v98, 48, v94
	v_mov_b32_e32 v99, v89
	v_add_u32_e32 v92, s11, v96
	v_ashrrev_i32_e32 v93, 31, v92
	s_waitcnt vmcnt(0)
	ds_write_b128 v39, v[2:5]
	ds_write2_b64 v41, v[6:7], v[8:9] offset1:2
	ds_write_b128 v39, v[10:13] offset:8192
	ds_write2_b64 v40, v[14:15], v[16:17] offset1:2
	ds_write_b128 v39, v[18:21] offset:16384
	v_lshlrev_b32_e32 v2, 1, v36
	v_and_b32_e32 v2, 62, v2
	v_and_b32_e32 v3, 0xfffff00, v36
	v_or3_b32 v2, v3, v2, v42
	v_lshl_add_u32 v2, v2, 4, v38
	v_add_u32_e32 v2, 0x8000, v2
	ds_write2_b64 v2, v[22:23], v[24:25] offset1:2
	ds_write_b128 v39, v[26:29] offset:24576
	v_lshlrev_b32_e32 v2, 1, v37
	v_and_b32_e32 v2, 62, v2
	v_and_b32_e32 v3, 0xfffff00, v37
	v_or3_b32 v2, v3, v2, v42
	v_lshl_add_u32 v2, v2, 4, v38
	v_add_u32_e32 v2, 0x8000, v2
	ds_write2_b64 v2, v[30:31], v[32:33] offset1:2
	v_lshl_add_u64 v[2:3], v[34:35], 0, v[98:99]
	v_lshl_add_u64 v[90:91], v[2:3], 0, s[22:23]
	v_lshlrev_b64 v[2:3], 17, v[92:93]
	v_lshl_add_u64 v[108:109], v[90:91], 0, v[2:3]
	s_waitcnt lgkmcnt(0)
	s_barrier
	global_load_dwordx4 v[54:57], v[108:109], off
	global_load_dwordx4 v[2:5], v[108:109], off offset:64
	v_cmp_lt_i32_e32 vcc, v146, v147
	v_ashrrev_i32_e32 v97, 31, v96
	s_mov_b32 s5, s17
	v_cndmask_b32_e32 v6, v145, v146, vcc
	v_cmp_lt_i32_e32 vcc, v148, v147
	v_lshlrev_b32_e32 v93, 2, v6
	v_lshl_or_b32 v100, s8, 12, v113
	v_cndmask_b32_e32 v6, v145, v148, vcc
	v_lshlrev_b32_e32 v157, 2, v6
	v_lshlrev_b64 v[6:7], 17, v[96:97]
	v_lshl_add_u64 v[6:7], s[4:5], 0, v[6:7]
	v_lshlrev_b32_e32 v8, 11, v100
	v_mov_b32_e32 v9, v89
	s_add_u32 s4, s16, 0x152c2000
	v_ashrrev_i32_e32 v111, 31, v110
	v_lshl_add_u64 v[114:115], v[6:7], 0, v[8:9]
	s_addc_u32 s5, 0, 0
	v_lshlrev_b64 v[104:105], 9, v[110:111]
	v_lshlrev_b32_e32 v6, 2, v110
	v_lshl_add_u64 v[116:117], s[4:5], 0, v[104:105]
	s_add_u32 s4, s58, 0x53c2400
	v_ashrrev_i32_e32 v7, 31, v6
	v_and_b32_e32 v112, 63, v94
	s_addc_u32 s5, 0, 0
	v_lshlrev_b64 v[106:107], 9, v[6:7]
	v_bfe_u32 v99, v94, 4, 2
	v_lshlrev_b32_e32 v102, 3, v112
	v_lshl_add_u64 v[118:119], s[4:5], 0, v[106:107]
	s_mov_b32 s59, s17
	v_lshlrev_b32_e32 v88, 3, v99
	v_lshl_add_u32 v127, v112, 4, 0
	v_mov_b32_e32 v101, v89
	v_or3_b32 v114, v114, s50, v98
	v_mov_b32_e32 v103, v89
	v_or_b32_e32 v116, v116, v102
	v_or_b32_e32 v118, v118, v102
	s_mov_b32 s4, 7
	s_waitcnt vmcnt(0)
.LBB0_667:
	ds_read_b128 v[6:9], v127
	ds_read_b128 v[14:17], v127 offset:1024
	ds_read_b128 v[18:21], v127 offset:2048
	ds_read_b128 v[22:25], v127 offset:3072
	ds_read_b128 v[26:29], v127 offset:4096
	ds_read_b128 v[30:33], v127 offset:5120
	ds_read_b128 v[34:37], v127 offset:6144
	ds_read_b128 v[38:41], v127 offset:7168
	ds_read_b128 v[42:45], v127 offset:8192
	ds_read_b128 v[120:123], v127 offset:9216
	v_mov_b64_e32 v[10:11], v[54:55]
	v_mov_b64_e32 v[12:13], v[56:57]
	s_add_i32 s4, s4, -1
	v_lshl_add_u64 v[124:125], s[38:39], 0, v[116:117]
	s_waitcnt lgkmcnt(1)
	v_mfma_f32_16x16x32_bf16 v[128:131], v[42:45], v[10:13], 0
	ds_read_b128 v[42:45], v127 offset:10240
	ds_read_b128 v[132:135], v127 offset:11264
	v_lshl_add_u64 v[116:117], v[116:117], 0, s[44:45]
	s_cmp_eq_u32 s4, 0
	s_waitcnt lgkmcnt(1)
	v_mfma_f32_16x16x32_bf16 v[136:139], v[42:45], v[10:13], 0
	ds_read_b128 v[42:45], v127 offset:12288
	ds_read_b128 v[158:161], v127 offset:13312
	s_waitcnt lgkmcnt(1)
	v_mfma_f32_16x16x32_bf16 v[162:165], v[42:45], v[10:13], 0
	ds_read_b128 v[42:45], v127 offset:14336
	ds_read_b128 v[166:169], v127 offset:15360
	s_waitcnt lgkmcnt(1)
	v_mfma_f32_16x16x32_bf16 v[170:173], v[42:45], v[10:13], 0
	ds_read_b128 v[42:45], v127 offset:16384
	ds_read_b128 v[174:177], v127 offset:17408
	s_waitcnt lgkmcnt(1)
	v_mfma_f32_16x16x32_bf16 v[178:181], v[42:45], v[10:13], 0
	ds_read_b128 v[42:45], v127 offset:18432
	ds_read_b128 v[182:185], v127 offset:19456
	s_waitcnt lgkmcnt(1)
	v_mfma_f32_16x16x32_bf16 v[186:189], v[42:45], v[10:13], 0
	ds_read_b128 v[42:45], v127 offset:20480
	ds_read_b128 v[190:193], v127 offset:21504
	s_waitcnt lgkmcnt(1)
	v_mfma_f32_16x16x32_bf16 v[194:197], v[42:45], v[10:13], 0
	ds_read_b128 v[42:45], v127 offset:22528
	ds_read_b128 v[198:201], v127 offset:23552
	s_waitcnt lgkmcnt(1)
	v_mfma_f32_16x16x32_bf16 v[202:205], v[42:45], v[10:13], 0
	ds_read_b128 v[42:45], v127 offset:24576
	ds_read_b128 v[54:57], v127 offset:25600
	s_waitcnt lgkmcnt(1)
	v_mfma_f32_16x16x32_bf16 v[66:69], v[42:45], v[10:13], 0
	ds_read_b128 v[42:45], v127 offset:26624
	ds_read_b128 v[58:61], v127 offset:27648
	s_waitcnt lgkmcnt(1)
	v_mfma_f32_16x16x32_bf16 v[70:73], v[42:45], v[10:13], 0
	ds_read_b128 v[42:45], v127 offset:28672
	ds_read_b128 v[74:77], v127 offset:29696
	v_mfma_f32_16x16x32_bf16 v[6:9], v[6:9], v[10:13], 0
	v_mfma_f32_16x16x32_bf16 v[18:21], v[18:21], v[10:13], 0
	s_waitcnt lgkmcnt(1)
	v_mfma_f32_16x16x32_bf16 v[82:85], v[42:45], v[10:13], 0
	ds_read_b128 v[42:45], v127 offset:30720
	ds_read_b128 v[62:65], v127 offset:31744
	v_mfma_f32_16x16x32_bf16 v[26:29], v[26:29], v[10:13], 0
	v_mfma_f32_16x16x32_bf16 v[34:37], v[34:37], v[10:13], 0
	s_waitcnt lgkmcnt(1)
	v_mfma_f32_16x16x32_bf16 v[78:81], v[42:45], v[10:13], 0
	v_mfma_f32_16x16x32_bf16 v[50:53], v[14:17], v[2:5], v[6:9]
	v_mfma_f32_16x16x32_bf16 v[46:49], v[22:25], v[2:5], v[18:21]
	v_mfma_f32_16x16x32_bf16 v[42:45], v[30:33], v[2:5], v[26:29]
	v_mfma_f32_16x16x32_bf16 v[38:41], v[38:41], v[2:5], v[34:37]
	v_mfma_f32_16x16x32_bf16 v[34:37], v[120:123], v[2:5], v[128:131]
	v_lshl_add_u64 v[120:121], s[38:39], 0, v[114:115]
	v_lshl_add_u64 v[122:123], s[38:39], 0, v[118:119]
	v_lshl_add_u64 v[114:115], v[114:115], 0, s[28:29]
	v_mfma_f32_16x16x32_bf16 v[30:33], v[132:135], v[2:5], v[136:139]
	v_lshl_add_u64 v[118:119], v[118:119], 0, s[46:47]
	v_mfma_f32_16x16x32_bf16 v[26:29], v[158:161], v[2:5], v[162:165]
	v_mfma_f32_16x16x32_bf16 v[22:25], v[166:169], v[2:5], v[170:173]
	v_mfma_f32_16x16x32_bf16 v[18:21], v[174:177], v[2:5], v[178:181]
	v_mfma_f32_16x16x32_bf16 v[14:17], v[182:185], v[2:5], v[186:189]
	v_mfma_f32_16x16x32_bf16 v[6:9], v[190:193], v[2:5], v[194:197]
	v_mfma_f32_16x16x32_bf16 v[10:13], v[198:201], v[2:5], v[202:205]
	v_mfma_f32_16x16x32_bf16 v[66:69], v[54:57], v[2:5], v[66:69]
	v_mfma_f32_16x16x32_bf16 v[70:73], v[58:61], v[2:5], v[70:73]
	v_add_co_u32_e32 v58, vcc, 0x9802000, v120
	v_mfma_f32_16x16x32_bf16 v[74:77], v[74:77], v[2:5], v[82:85]
	s_nop 0
	v_addc_co_u32_e32 v59, vcc, 0, v121, vcc
	global_load_dwordx4 v[54:57], v[58:59], off offset:1024
	s_nop 0
	global_load_dwordx4 v[58:61], v[58:59], off offset:1088
	s_waitcnt lgkmcnt(0)
	v_mfma_f32_16x16x32_bf16 v[2:5], v[62:65], v[2:5], v[78:81]
	v_max_f32_e32 v62, v48, v48
	v_max_f32_e32 v63, v52, v52
	v_max_f32_e32 v64, v49, v49
	v_max_f32_e32 v65, v53, v53
	v_max_f32_e32 v78, v46, v46
	v_max_f32_e32 v79, v50, v50
	v_max_f32_e32 v80, v47, v47
	v_max_f32_e32 v81, v51, v51
	v_max_f32_e32 v62, v63, v62
	v_max_f32_e32 v63, v65, v64
	v_max_f32_e32 v64, v79, v78
	v_max_f32_e32 v65, v81, v80
	v_max3_f32 v63, v63, v45, v41
	v_max3_f32 v62, v62, v44, v40
	v_max3_f32 v65, v65, v43, v39
	v_max3_f32 v64, v64, v42, v38
	v_max3_f32 v62, v62, v36, v32
	v_max3_f32 v63, v63, v37, v33
	v_max3_f32 v64, v64, v34, v30
	v_max3_f32 v65, v65, v35, v31
	v_max3_f32 v63, v63, v29, v25
	v_max3_f32 v62, v62, v28, v24
	v_max3_f32 v65, v65, v27, v23
	v_max3_f32 v64, v64, v26, v22
	v_max3_f32 v62, v62, v20, v16
	v_max3_f32 v63, v63, v21, v17
	v_max3_f32 v64, v64, v18, v14
	v_max3_f32 v65, v65, v19, v15
	v_max3_f32 v63, v63, v9, v13
	v_max3_f32 v62, v62, v8, v12
	v_max3_f32 v65, v65, v7, v11
	v_max3_f32 v64, v64, v6, v10
	v_max3_f32 v62, v62, v68, v72
	v_max3_f32 v63, v63, v69, v73
	v_max3_f32 v64, v64, v66, v70
	v_max3_f32 v65, v65, v67, v71
	v_max3_f32 v63, v63, v77, v5
	v_max3_f32 v62, v62, v76, v4
	v_max3_f32 v65, v65, v75, v3
	v_max3_f32 v64, v64, v74, v2
	v_max_f32_e32 v62, v62, v63
	v_max3_f32 v62, v64, v65, v62
	ds_bpermute_b32 v63, v93, v62
	s_waitcnt lgkmcnt(0)
	v_max_f32_e32 v63, v63, v63
	v_max_f32_e32 v62, v62, v63
	ds_bpermute_b32 v63, v157, v62
	s_waitcnt lgkmcnt(0)
	v_max_f32_e32 v63, v63, v63
	v_max_f32_e32 v62, v62, v63
	v_mul_f32_e32 v62, 0x3e38aa3b, v62
	v_pk_fma_f32 v[52:53], v[52:53], s[24:25], v[62:63] op_sel_hi:[1,0,0] neg_lo:[0,0,1] neg_hi:[0,0,1]
	v_pk_fma_f32 v[50:51], v[50:51], s[24:25], v[62:63] op_sel_hi:[1,0,0] neg_lo:[0,0,1] neg_hi:[0,0,1]
	v_pk_fma_f32 v[48:49], v[48:49], s[24:25], v[62:63] op_sel_hi:[1,0,0] neg_lo:[0,0,1] neg_hi:[0,0,1]
	v_pk_fma_f32 v[46:47], v[46:47], s[24:25], v[62:63] op_sel_hi:[1,0,0] neg_lo:[0,0,1] neg_hi:[0,0,1]
	v_pk_fma_f32 v[20:21], v[20:21], s[24:25], v[62:63] op_sel_hi:[1,0,0] neg_lo:[0,0,1] neg_hi:[0,0,1]
	v_pk_fma_f32 v[18:19], v[18:19], s[24:25], v[62:63] op_sel_hi:[1,0,0] neg_lo:[0,0,1] neg_hi:[0,0,1]
	v_pk_fma_f32 v[16:17], v[16:17], s[24:25], v[62:63] op_sel_hi:[1,0,0] neg_lo:[0,0,1] neg_hi:[0,0,1]
	v_pk_fma_f32 v[14:15], v[14:15], s[24:25], v[62:63] op_sel_hi:[1,0,0] neg_lo:[0,0,1] neg_hi:[0,0,1]
	v_pk_fma_f32 v[8:9], v[8:9], s[24:25], v[62:63] op_sel_hi:[1,0,0] neg_lo:[0,0,1] neg_hi:[0,0,1]
	v_pk_fma_f32 v[6:7], v[6:7], s[24:25], v[62:63] op_sel_hi:[1,0,0] neg_lo:[0,0,1] neg_hi:[0,0,1]
	v_pk_fma_f32 v[12:13], v[12:13], s[24:25], v[62:63] op_sel_hi:[1,0,0] neg_lo:[0,0,1] neg_hi:[0,0,1]
	v_pk_fma_f32 v[10:11], v[10:11], s[24:25], v[62:63] op_sel_hi:[1,0,0] neg_lo:[0,0,1] neg_hi:[0,0,1]
	v_pk_fma_f32 v[4:5], v[4:5], s[24:25], v[62:63] op_sel_hi:[1,0,0] neg_lo:[0,0,1] neg_hi:[0,0,1]
	v_pk_fma_f32 v[2:3], v[2:3], s[24:25], v[62:63] op_sel_hi:[1,0,0] neg_lo:[0,0,1] neg_hi:[0,0,1]
	v_exp_f32_e32 v50, v50
	v_exp_f32_e32 v51, v51
	v_exp_f32_e32 v52, v52
	v_exp_f32_e32 v53, v53
	v_exp_f32_e32 v84, v46
	v_exp_f32_e32 v85, v47
	v_exp_f32_e32 v120, v48
	v_exp_f32_e32 v121, v49
	v_exp_f32_e32 v194, v18
	v_exp_f32_e32 v195, v19
	v_exp_f32_e32 v196, v20
	v_exp_f32_e32 v197, v21
	v_exp_f32_e32 v198, v14
	v_exp_f32_e32 v199, v15
	v_exp_f32_e32 v200, v16
	v_exp_f32_e32 v201, v17
	v_exp_f32_e32 v202, v6
	v_exp_f32_e32 v203, v7
	v_exp_f32_e32 v204, v8
	v_exp_f32_e32 v205, v9
	v_exp_f32_e32 v206, v10
	v_exp_f32_e32 v207, v11
	v_exp_f32_e32 v208, v12
	v_exp_f32_e32 v209, v13
	v_exp_f32_e32 v222, v2
	v_exp_f32_e32 v223, v3
	v_exp_f32_e32 v224, v4
	v_exp_f32_e32 v225, v5
	v_cvt_pk_bf16_f32 v2, v50, v51
	v_cvt_pk_bf16_f32 v3, v52, v53
	v_cvt_pk_bf16_f32 v4, v84, v85
	v_cvt_pk_bf16_f32 v5, v120, v121
	ds_read_b128 v[6:9], v127 offset:32768
	ds_read_b128 v[10:13], v127 offset:33792
	ds_read_b128 v[14:17], v127 offset:34816
	ds_read_b128 v[18:21], v127 offset:35840
	s_waitcnt lgkmcnt(3)
	v_mfma_f32_16x16x32_bf16 v[6:9], v[6:9], v[2:5], 0
	v_fma_f32 v44, v44, s24, -v62
	v_fma_f32 v45, v45, s24, -v62
	v_pk_fma_f32 v[42:43], v[42:43], s[24:25], v[62:63] op_sel_hi:[1,0,0] neg_lo:[0,0,1] neg_hi:[0,0,1]
	v_pk_fma_f32 v[40:41], v[40:41], s[24:25], v[62:63] op_sel_hi:[1,0,0] neg_lo:[0,0,1] neg_hi:[0,0,1]
	v_pk_fma_f32 v[38:39], v[38:39], s[24:25], v[62:63] op_sel_hi:[1,0,0] neg_lo:[0,0,1] neg_hi:[0,0,1]
	v_pk_fma_f32 v[36:37], v[36:37], s[24:25], v[62:63] op_sel_hi:[1,0,0] neg_lo:[0,0,1] neg_hi:[0,0,1]
	v_pk_fma_f32 v[34:35], v[34:35], s[24:25], v[62:63] op_sel_hi:[1,0,0] neg_lo:[0,0,1] neg_hi:[0,0,1]
	v_pk_fma_f32 v[32:33], v[32:33], s[24:25], v[62:63] op_sel_hi:[1,0,0] neg_lo:[0,0,1] neg_hi:[0,0,1]
	v_pk_fma_f32 v[30:31], v[30:31], s[24:25], v[62:63] op_sel_hi:[1,0,0] neg_lo:[0,0,1] neg_hi:[0,0,1]
	v_pk_fma_f32 v[28:29], v[28:29], s[24:25], v[62:63] op_sel_hi:[1,0,0] neg_lo:[0,0,1] neg_hi:[0,0,1]
	v_pk_fma_f32 v[26:27], v[26:27], s[24:25], v[62:63] op_sel_hi:[1,0,0] neg_lo:[0,0,1] neg_hi:[0,0,1]
	v_pk_fma_f32 v[24:25], v[24:25], s[24:25], v[62:63] op_sel_hi:[1,0,0] neg_lo:[0,0,1] neg_hi:[0,0,1]
	v_pk_fma_f32 v[22:23], v[22:23], s[24:25], v[62:63] op_sel_hi:[1,0,0] neg_lo:[0,0,1] neg_hi:[0,0,1]
	v_pk_fma_f32 v[64:65], v[68:69], s[24:25], v[62:63] op_sel_hi:[1,0,0] neg_lo:[0,0,1] neg_hi:[0,0,1]
	v_pk_fma_f32 v[66:67], v[66:67], s[24:25], v[62:63] op_sel_hi:[1,0,0] neg_lo:[0,0,1] neg_hi:[0,0,1]
	v_pk_fma_f32 v[68:69], v[72:73], s[24:25], v[62:63] op_sel_hi:[1,0,0] neg_lo:[0,0,1] neg_hi:[0,0,1]
	v_pk_fma_f32 v[70:71], v[70:71], s[24:25], v[62:63] op_sel_hi:[1,0,0] neg_lo:[0,0,1] neg_hi:[0,0,1]
	v_pk_fma_f32 v[72:73], v[76:77], s[24:25], v[62:63] op_sel_hi:[1,0,0] neg_lo:[0,0,1] neg_hi:[0,0,1]
	v_pk_fma_f32 v[74:75], v[74:75], s[24:25], v[62:63] op_sel_hi:[1,0,0] neg_lo:[0,0,1] neg_hi:[0,0,1]
	v_exp_f32_e32 v170, v42
	v_exp_f32_e32 v171, v43
	v_exp_f32_e32 v172, v44
	v_exp_f32_e32 v173, v45
	v_exp_f32_e32 v174, v38
	v_exp_f32_e32 v175, v39
	v_exp_f32_e32 v176, v40
	v_exp_f32_e32 v177, v41
	v_exp_f32_e32 v178, v34
	v_exp_f32_e32 v179, v35
	v_exp_f32_e32 v180, v36
	v_exp_f32_e32 v181, v37
	v_exp_f32_e32 v182, v30
	v_exp_f32_e32 v183, v31
	v_exp_f32_e32 v184, v32
	v_exp_f32_e32 v185, v33
	v_exp_f32_e32 v186, v26
	v_exp_f32_e32 v187, v27
	v_exp_f32_e32 v188, v28
	v_exp_f32_e32 v189, v29
	v_exp_f32_e32 v190, v22
	v_exp_f32_e32 v191, v23
	v_exp_f32_e32 v192, v24
	v_exp_f32_e32 v193, v25
	v_cvt_pk_bf16_f32 v22, v170, v171
	v_cvt_pk_bf16_f32 v23, v172, v173
	v_cvt_pk_bf16_f32 v24, v174, v175
	v_cvt_pk_bf16_f32 v25, v176, v177
	ds_read_b128 v[26:29], v127 offset:36864
	ds_read_b128 v[30:33], v127 offset:37888
	ds_read_b128 v[34:37], v127 offset:38912
	ds_read_b128 v[38:41], v127 offset:39936
	v_exp_f32_e32 v210, v66
	v_exp_f32_e32 v211, v67
	v_exp_f32_e32 v212, v64
	v_exp_f32_e32 v213, v65
	v_exp_f32_e32 v214, v70
	v_exp_f32_e32 v215, v71
	v_exp_f32_e32 v216, v68
	v_exp_f32_e32 v217, v69
	v_exp_f32_e32 v218, v74
	v_exp_f32_e32 v219, v75
	v_exp_f32_e32 v220, v72
	v_exp_f32_e32 v221, v73
	v_pk_add_f32 v[226:227], v[50:51], 0 op_sel_hi:[1,0]
	v_pk_add_f32 v[228:229], v[52:53], 0 op_sel_hi:[1,0]
	v_cvt_pk_bf16_f32 v42, v178, v179
	v_cvt_pk_bf16_f32 v43, v180, v181
	v_cvt_pk_bf16_f32 v44, v182, v183
	v_cvt_pk_bf16_f32 v45, v184, v185
	s_waitcnt lgkmcnt(6)
	v_mfma_f32_16x16x32_bf16 v[10:13], v[10:13], v[2:5], 0
	ds_read_b128 v[46:49], v127 offset:40960
	ds_read_b128 v[50:53], v127 offset:41984
	ds_read_b128 v[64:67], v127 offset:43008
	ds_read_b128 v[68:71], v127 offset:44032
	v_cvt_pk_bf16_f32 v72, v186, v187
	s_waitcnt lgkmcnt(9)
	v_mfma_f32_16x16x32_bf16 v[14:17], v[14:17], v[2:5], 0
	v_cvt_pk_bf16_f32 v73, v188, v189
	v_cvt_pk_bf16_f32 v74, v190, v191
	v_cvt_pk_bf16_f32 v75, v192, v193
	s_waitcnt lgkmcnt(8)
	v_mfma_f32_16x16x32_bf16 v[2:5], v[18:21], v[2:5], 0
	ds_read_b128 v[18:21], v127 offset:45056
	v_pk_add_f32 v[120:121], v[120:121], v[228:229]
	s_waitcnt lgkmcnt(8)
	v_mfma_f32_16x16x32_bf16 v[6:9], v[26:29], v[22:25], v[6:9]
	ds_read_b128 v[26:29], v127 offset:46080
	ds_read_b128 v[76:79], v127 offset:47104
	ds_read_b128 v[80:83], v127 offset:48128
	s_waitcnt lgkmcnt(9)
	v_mfma_f32_16x16x32_bf16 v[14:17], v[34:37], v[22:25], v[14:17]
	s_waitcnt lgkmcnt(7)
	v_mfma_f32_16x16x32_bf16 v[6:9], v[46:49], v[42:45], v[6:9]
	v_mfma_f32_16x16x32_bf16 v[10:13], v[30:33], v[22:25], v[10:13]
	v_cvt_pk_bf16_f32 v30, v194, v195
	v_cvt_pk_bf16_f32 v31, v196, v197
	v_cvt_pk_bf16_f32 v32, v198, v199
	s_waitcnt lgkmcnt(5)
	v_mfma_f32_16x16x32_bf16 v[14:17], v[64:67], v[42:45], v[14:17]
	v_cvt_pk_bf16_f32 v33, v200, v201
	ds_read_b128 v[34:37], v127 offset:49152
	ds_read_b128 v[128:131], v127 offset:50176
	s_waitcnt lgkmcnt(5)
	v_mfma_f32_16x16x32_bf16 v[6:9], v[18:21], v[72:75], v[6:9]
	v_mfma_f32_16x16x32_bf16 v[2:5], v[38:41], v[22:25], v[2:5]
	ds_read_b128 v[22:25], v127 offset:51200
	ds_read_b128 v[38:41], v127 offset:52224
	v_cvt_pk_bf16_f32 v132, v202, v203
	v_cvt_pk_bf16_f32 v133, v204, v205
	v_mfma_f32_16x16x32_bf16 v[10:13], v[50:53], v[42:45], v[10:13]
	v_cvt_pk_bf16_f32 v134, v206, v207
	v_cvt_pk_bf16_f32 v135, v208, v209
	ds_read_b128 v[46:49], v127 offset:53248
	ds_read_b128 v[50:53], v127 offset:54272
	ds_read_b128 v[136:139], v127 offset:55296
	s_waitcnt lgkmcnt(8)
	v_mfma_f32_16x16x32_bf16 v[14:17], v[76:79], v[72:75], v[14:17]
	ds_read_b128 v[64:67], v127 offset:56320
	v_cvt_pk_bf16_f32 v158, v210, v211
	v_cvt_pk_bf16_f32 v159, v212, v213
	s_waitcnt lgkmcnt(7)
	v_mfma_f32_16x16x32_bf16 v[6:9], v[34:37], v[30:33], v[6:9]
	v_add_f32_e64 v34, v84, v226
	v_add_f32_e64 v35, v85, v227
	v_pk_add_f32 v[36:37], v[172:173], v[120:121]
	v_pk_add_f32 v[34:35], v[170:171], v[34:35]
	v_mfma_f32_16x16x32_bf16 v[2:5], v[68:71], v[42:45], v[2:5]
	v_add_f32_e64 v36, v176, v36
	v_add_f32_e64 v37, v177, v37
	v_pk_add_f32 v[34:35], v[174:175], v[34:35]
	v_cvt_pk_bf16_f32 v160, v214, v215
	v_mfma_f32_16x16x32_bf16 v[10:13], v[26:29], v[72:75], v[10:13]
	v_add_f32_e64 v34, v178, v34
	v_add_f32_e64 v35, v179, v35
	v_cvt_pk_bf16_f32 v161, v216, v217
	ds_read_b128 v[42:45], v127 offset:57344
	s_waitcnt lgkmcnt(6)
	v_mfma_f32_16x16x32_bf16 v[14:17], v[22:25], v[30:33], v[14:17]
	v_add_f32_e64 v22, v180, v36
	v_add_f32_e64 v23, v181, v37
	v_pk_add_f32 v[24:25], v[182:183], v[34:35]
	v_pk_add_f32 v[22:23], v[184:185], v[22:23]
	v_pk_add_f32 v[24:25], v[186:187], v[24:25]
	v_pk_add_f32 v[22:23], v[188:189], v[22:23]
	v_mfma_f32_16x16x32_bf16 v[2:5], v[80:83], v[72:75], v[2:5]
	v_add_f32_e64 v22, v192, v22
	v_add_f32_e64 v23, v193, v23
	v_pk_add_f32 v[24:25], v[190:191], v[24:25]
	v_pk_add_f32 v[22:23], v[196:197], v[22:23]
	v_mfma_f32_16x16x32_bf16 v[10:13], v[128:131], v[30:33], v[10:13]
	v_add_f32_e64 v24, v194, v24
	v_add_f32_e64 v25, v195, v25
	v_pk_add_f32 v[22:23], v[200:201], v[22:23]
	v_pk_add_f32 v[24:25], v[198:199], v[24:25]
	v_pk_add_f32 v[22:23], v[204:205], v[22:23]
	v_pk_add_f32 v[24:25], v[202:203], v[24:25]
	s_waitcnt lgkmcnt(5)
	v_mfma_f32_16x16x32_bf16 v[2:5], v[38:41], v[30:33], v[2:5]
	v_add_f32_e64 v22, v208, v22
	v_add_f32_e64 v23, v209, v23
	v_pk_add_f32 v[24:25], v[206:207], v[24:25]
	ds_read_b128 v[18:21], v127 offset:58368
	ds_read_b128 v[68:71], v127 offset:59392
	ds_read_b128 v[162:165], v127 offset:60416
	s_waitcnt lgkmcnt(6)
	v_mfma_f32_16x16x32_bf16 v[10:13], v[50:53], v[132:135], v[10:13]
	v_add_f32_e64 v24, v210, v24
	v_add_f32_e64 v25, v211, v25
	v_pk_add_f32 v[22:23], v[212:213], v[22:23]
	v_pk_add_f32 v[24:25], v[214:215], v[24:25]
	v_pk_add_f32 v[22:23], v[216:217], v[22:23]
	v_pk_add_f32 v[24:25], v[218:219], v[24:25]
	v_pk_add_f32 v[22:23], v[220:221], v[22:23]
	s_waitcnt lgkmcnt(4)
	v_mfma_f32_16x16x32_bf16 v[2:5], v[64:67], v[132:135], v[2:5]
	v_cvt_pk_bf16_f32 v26, v218, v219
	v_cvt_pk_bf16_f32 v27, v220, v221
	v_cvt_pk_bf16_f32 v28, v222, v223
	s_waitcnt lgkmcnt(2)
	v_mfma_f32_16x16x32_bf16 v[10:13], v[18:21], v[158:161], v[10:13]
	v_add_f32_e64 v18, v224, v22
	v_add_f32_e64 v19, v225, v23
	v_pk_add_f32 v[20:21], v[222:223], v[24:25]
	v_cvt_pk_bf16_f32 v29, v224, v225
	v_mfma_f32_16x16x32_bf16 v[6:9], v[46:49], v[132:135], v[6:9]
	v_pk_mov_b32 v[22:23], v[20:21], v[18:19] op_sel:[1,0]
	v_mov_b32_e32 v21, v19
	v_pk_add_f32 v[18:19], v[22:23], v[20:21]
	v_mfma_f32_16x16x32_bf16 v[14:17], v[136:139], v[132:135], v[14:17]
	v_add_f32_e32 v22, v18, v19
	ds_read_b128 v[76:79], v127 offset:61440
	ds_read_b128 v[166:169], v127 offset:62464
	ds_read_b128 v[72:75], v127 offset:63488
	ds_read_b128 v[80:83], v127 offset:64512
	s_waitcnt lgkmcnt(4)
	v_mfma_f32_16x16x32_bf16 v[18:21], v[162:165], v[158:161], v[2:5]
	s_nop 2
	ds_bpermute_b32 v2, v93, v22
	v_mfma_f32_16x16x32_bf16 v[6:9], v[42:45], v[158:161], v[6:9]
	s_waitcnt lgkmcnt(0)
	v_add_f32_e32 v2, v22, v2
	ds_bpermute_b32 v3, v157, v2
	v_mfma_f32_16x16x32_bf16 v[14:17], v[68:71], v[158:161], v[14:17]
	s_waitcnt lgkmcnt(0)
	v_add_f32_e32 v63, v2, v3
	v_div_scale_f32 v22, s[60:61], v63, v63, 1.0
	v_rcp_f32_e32 v24, v22
	v_div_scale_f32 v23, vcc, 1.0, v63, 1.0
	v_mfma_f32_16x16x32_bf16 v[6:9], v[76:79], v[26:29], v[6:9]
	v_fma_f32 v25, -v22, v24, 1.0
	v_fmac_f32_e32 v24, v25, v24
	v_mul_f32_e32 v25, v23, v24
	v_mfma_f32_16x16x32_bf16 v[10:13], v[166:169], v[26:29], v[10:13]
	s_waitcnt vmcnt(0)
	v_mov_b64_e32 v[2:3], v[58:59]
	v_mov_b64_e32 v[4:5], v[60:61]
	v_mfma_f32_16x16x32_bf16 v[14:17], v[72:75], v[26:29], v[14:17]
	v_mfma_f32_16x16x32_bf16 v[18:21], v[80:83], v[26:29], v[18:21]
	v_fma_f32 v26, -v22, v25, v23
	v_fmac_f32_e32 v25, v26, v24
	v_fma_f32 v22, -v22, v25, v23
	v_div_fmas_f32 v22, v22, v24, v25
	v_div_fixup_f32 v22, v22, v63, 1.0
	v_mul_f32_e32 v6, v22, v6
	v_mul_f32_e32 v7, v22, v7
	v_mul_f32_e32 v8, v22, v8
	v_mul_f32_e32 v9, v22, v9
	v_cvt_pk_bf16_f32 v6, v6, v7
	v_cvt_pk_bf16_f32 v7, v8, v9
	v_mul_f32_e32 v10, v22, v10
	v_mul_f32_e32 v11, v22, v11
	v_mul_f32_e32 v12, v22, v12
	v_mul_f32_e32 v13, v22, v13
	global_store_dwordx2 v[122:123], v[6:7], off offset:-1024
	v_cvt_pk_bf16_f32 v6, v10, v11
	v_cvt_pk_bf16_f32 v7, v12, v13
	v_mul_f32_e32 v14, v22, v14
	v_mul_f32_e32 v15, v22, v15
	v_mul_f32_e32 v16, v22, v16
	v_mul_f32_e32 v17, v22, v17
	global_store_dwordx2 v[122:123], v[6:7], off offset:-512
	v_cvt_pk_bf16_f32 v6, v14, v15
	v_cvt_pk_bf16_f32 v7, v16, v17
	v_mul_f32_e32 v18, v22, v18
	v_mul_f32_e32 v19, v22, v19
	v_mul_f32_e32 v20, v22, v20
	v_mul_f32_e32 v21, v22, v21
	global_store_dwordx2 v[122:123], v[6:7], off
	v_cvt_pk_bf16_f32 v6, v18, v19
	v_cvt_pk_bf16_f32 v7, v20, v21
	global_store_dwordx2 v[122:123], v[6:7], off offset:512
	global_store_dwordx2 v[124:125], v[62:63], off
	s_cbranch_scc0 .LBB0_667
	ds_read_b128 v[2:5], v127
	ds_read_b128 v[6:9], v127 offset:1024
	ds_read_b128 v[10:13], v127 offset:2048
	ds_read_b128 v[14:17], v127 offset:3072
	s_lshl_b32 s7, s6, 17
	s_lshl_b32 s4, s6, 15
	s_waitcnt lgkmcnt(3)
	v_mfma_f32_16x16x32_bf16 v[2:5], v[2:5], v[54:57], 0
	s_add_u32 s4, s14, s4
	s_addc_u32 s5, s15, 0
	s_add_u32 s6, s69, s7
	s_waitcnt lgkmcnt(2)
	v_mfma_f32_16x16x32_bf16 v[28:31], v[6:9], v[58:61], v[2:5]
	ds_read_b128 v[6:9], v127 offset:5120
	s_addc_u32 s7, s72, 0
	s_nop 0
	ds_read_b128 v[2:5], v127 offset:4096
	s_waitcnt lgkmcnt(3)
	v_mfma_f32_16x16x32_bf16 v[10:13], v[10:13], v[54:57], 0
	s_waitcnt lgkmcnt(2)
	v_mfma_f32_16x16x32_bf16 v[32:35], v[14:17], v[58:61], v[10:13]
	s_waitcnt lgkmcnt(0)
	v_mfma_f32_16x16x32_bf16 v[2:5], v[2:5], v[54:57], 0
	s_nop 3
	ds_read_b128 v[10:13], v127 offset:6144
	v_mfma_f32_16x16x32_bf16 v[40:43], v[6:9], v[58:61], v[2:5]
	s_nop 2
	ds_read_b128 v[2:5], v127 offset:7168
	s_waitcnt lgkmcnt(1)
	v_mfma_f32_16x16x32_bf16 v[6:9], v[10:13], v[54:57], 0
	ds_read_b128 v[10:13], v127 offset:8192
	s_waitcnt lgkmcnt(1)
	v_mfma_f32_16x16x32_bf16 v[44:47], v[2:5], v[58:61], v[6:9]
	ds_read_b128 v[2:5], v127 offset:9216
	s_waitcnt lgkmcnt(1)
	v_mfma_f32_16x16x32_bf16 v[6:9], v[10:13], v[54:57], 0
	ds_read_b128 v[10:13], v127 offset:10240
	s_waitcnt lgkmcnt(1)
	v_mfma_f32_16x16x32_bf16 v[48:51], v[2:5], v[58:61], v[6:9]
	ds_read_b128 v[2:5], v127 offset:11264
	s_waitcnt lgkmcnt(1)
	v_mfma_f32_16x16x32_bf16 v[6:9], v[10:13], v[54:57], 0
	ds_read_b128 v[10:13], v127 offset:12288
	s_waitcnt lgkmcnt(1)
	v_mfma_f32_16x16x32_bf16 v[62:65], v[2:5], v[58:61], v[6:9]
	ds_read_b128 v[2:5], v127 offset:13312
	s_waitcnt lgkmcnt(1)
	v_mfma_f32_16x16x32_bf16 v[6:9], v[10:13], v[54:57], 0
	ds_read_b128 v[10:13], v127 offset:14336
	s_waitcnt lgkmcnt(1)
	v_mfma_f32_16x16x32_bf16 v[66:69], v[2:5], v[58:61], v[6:9]
	ds_read_b128 v[2:5], v127 offset:15360
	s_waitcnt lgkmcnt(1)
	v_mfma_f32_16x16x32_bf16 v[6:9], v[10:13], v[54:57], 0
	ds_read_b128 v[10:13], v127 offset:16384
	s_waitcnt lgkmcnt(1)
	v_mfma_f32_16x16x32_bf16 v[70:73], v[2:5], v[58:61], v[6:9]
	ds_read_b128 v[2:5], v127 offset:17408
	s_nop 3
	ds_read_b128 v[6:9], v127 offset:18432
	ds_read_b128 v[14:17], v127 offset:19456
	ds_read_b128 v[18:21], v127 offset:20480
	ds_read_b128 v[22:25], v127 offset:21504
	ds_read_b128 v[36:39], v127 offset:22528
	ds_read_b128 v[74:77], v127 offset:23552
	s_waitcnt lgkmcnt(5)
	v_mfma_f32_16x16x32_bf16 v[6:9], v[6:9], v[54:57], 0
	s_waitcnt lgkmcnt(4)
	v_mfma_f32_16x16x32_bf16 v[136:139], v[14:17], v[58:61], v[6:9]
	v_max_f32_e32 v15, v35, v35
	v_max_f32_e32 v16, v31, v31
	v_max_f32_e32 v15, v16, v15
	s_nop 2
	v_max_f32_e32 v6, v34, v34
	v_max_f32_e32 v7, v30, v30
	v_mfma_f32_16x16x32_bf16 v[10:13], v[10:13], v[54:57], 0
	v_max_f32_e32 v14, v7, v6
	v_max_f32_e32 v17, v33, v33
	s_waitcnt lgkmcnt(3)
	v_mfma_f32_16x16x32_bf16 v[6:9], v[18:21], v[54:57], 0
	v_max_f32_e32 v18, v29, v29
	v_max_f32_e32 v17, v18, v17
	v_mfma_f32_16x16x32_bf16 v[78:81], v[2:5], v[58:61], v[10:13]
	ds_read_b128 v[2:5], v127 offset:24576
	s_nop 1
	ds_read_b128 v[10:13], v127 offset:25600
	ds_read_b128 v[82:85], v127 offset:26624
	ds_read_b128 v[114:117], v127 offset:27648
	ds_read_b128 v[118:121], v127 offset:28672
	ds_read_b128 v[122:125], v127 offset:29696
	ds_read_b128 v[128:131], v127 offset:30720
	ds_read_b128 v[132:135], v127 offset:31744
	s_waitcnt lgkmcnt(10)
	v_mfma_f32_16x16x32_bf16 v[22:25], v[22:25], v[58:61], v[6:9]
	s_nop 2
	v_max_f32_e32 v6, v32, v32
	v_max_f32_e32 v7, v28, v28
	v_max_f32_e32 v16, v7, v6
	s_waitcnt lgkmcnt(9)
	v_mfma_f32_16x16x32_bf16 v[6:9], v[36:39], v[54:57], 0
	s_waitcnt lgkmcnt(7)
	v_mfma_f32_16x16x32_bf16 v[2:5], v[2:5], v[54:57], 0
	v_mfma_f32_16x16x32_bf16 v[18:21], v[74:77], v[58:61], v[6:9]
	s_nop 4
	v_max3_f32 v6, v17, v41, v45
	v_max3_f32 v7, v16, v40, v44
	v_max3_f32 v8, v15, v43, v47
	v_max3_f32 v9, v14, v42, v46
	s_waitcnt lgkmcnt(6)
	v_mfma_f32_16x16x32_bf16 v[14:17], v[10:13], v[58:61], v[2:5]
	v_max3_f32 v9, v9, v50, v64
	v_max3_f32 v7, v7, v48, v62
	v_max3_f32 v8, v8, v51, v65
	v_max3_f32 v2, v6, v49, v63
	v_max3_f32 v6, v2, v67, v71
	s_waitcnt lgkmcnt(5)
	v_mfma_f32_16x16x32_bf16 v[2:5], v[82:85], v[54:57], 0
	v_max3_f32 v7, v7, v66, v70
	v_max3_f32 v9, v9, v68, v72
	v_max3_f32 v8, v8, v69, v73
	s_waitcnt lgkmcnt(4)
	v_mfma_f32_16x16x32_bf16 v[10:13], v[114:117], v[58:61], v[2:5]
	v_max3_f32 v26, v9, v80, v138
	v_max3_f32 v7, v7, v78, v136
	v_max3_f32 v6, v6, v79, v137
	s_waitcnt lgkmcnt(3)
	v_mfma_f32_16x16x32_bf16 v[2:5], v[118:121], v[54:57], 0
	v_max3_f32 v27, v8, v81, v139
	v_max3_f32 v36, v6, v23, v19
	v_max3_f32 v37, v7, v22, v18
	s_waitcnt lgkmcnt(2)
	v_mfma_f32_16x16x32_bf16 v[6:9], v[122:125], v[58:61], v[2:5]
	v_max3_f32 v27, v27, v25, v21
	v_max3_f32 v27, v27, v17, v13
	v_max3_f32 v37, v37, v14, v10
	v_max3_f32 v2, v26, v24, v20
	v_max3_f32 v26, v2, v16, v12
	s_waitcnt lgkmcnt(1)
	v_mfma_f32_16x16x32_bf16 v[2:5], v[128:131], v[54:57], 0
	v_max3_f32 v36, v36, v15, v11
	s_waitcnt lgkmcnt(0)
	v_mfma_f32_16x16x32_bf16 v[2:5], v[132:135], v[58:61], v[2:5]
	s_nop 7
	v_max3_f32 v27, v27, v9, v5
	v_max3_f32 v26, v26, v8, v4
	v_max3_f32 v36, v36, v7, v3
	v_max3_f32 v37, v37, v6, v2
	v_max_f32_e32 v26, v26, v27
	v_max3_f32 v26, v37, v36, v26
	ds_bpermute_b32 v27, v93, v26
	s_waitcnt lgkmcnt(0)
	v_max_f32_e32 v27, v27, v27
	v_max_f32_e32 v26, v26, v27
	ds_bpermute_b32 v27, v157, v26
	s_waitcnt lgkmcnt(0)
	v_max_f32_e32 v27, v27, v27
	v_max_f32_e32 v26, v26, v27
	v_mul_f32_e32 v26, 0x3e38aa3b, v26
	v_pk_fma_f32 v[30:31], v[30:31], s[24:25], v[26:27] op_sel_hi:[1,0,0] neg_lo:[0,0,1] neg_hi:[0,0,1]
	v_pk_fma_f32 v[28:29], v[28:29], s[24:25], v[26:27] op_sel_hi:[1,0,0] neg_lo:[0,0,1] neg_hi:[0,0,1]
	v_exp_f32_e32 v30, v30
	v_exp_f32_e32 v28, v28
	v_exp_f32_e32 v29, v29
	v_exp_f32_e32 v31, v31
	v_pk_fma_f32 v[34:35], v[34:35], s[24:25], v[26:27] op_sel_hi:[1,0,0] neg_lo:[0,0,1] neg_hi:[0,0,1]
	v_pk_fma_f32 v[32:33], v[32:33], s[24:25], v[26:27] op_sel_hi:[1,0,0] neg_lo:[0,0,1] neg_hi:[0,0,1]
	v_exp_f32_e32 v38, v34
	v_exp_f32_e32 v36, v32
	v_exp_f32_e32 v37, v33
	v_exp_f32_e32 v39, v35
	v_pk_fma_f32 v[34:35], v[42:43], s[24:25], v[26:27] op_sel_hi:[1,0,0] neg_lo:[0,0,1] neg_hi:[0,0,1]
	v_pk_fma_f32 v[32:33], v[40:41], s[24:25], v[26:27] op_sel_hi:[1,0,0] neg_lo:[0,0,1] neg_hi:[0,0,1]
	v_exp_f32_e32 v34, v34
	v_exp_f32_e32 v32, v32
	v_exp_f32_e32 v33, v33
	v_exp_f32_e32 v35, v35
	v_pk_add_f32 v[52:53], v[28:29], 0 op_sel_hi:[1,0]
	v_pk_add_f32 v[54:55], v[30:31], 0 op_sel_hi:[1,0]
	v_pk_add_f32 v[42:43], v[36:37], v[52:53]
	v_pk_add_f32 v[40:41], v[38:39], v[54:55]
	v_pk_add_f32 v[52:53], v[32:33], v[42:43]
	v_pk_add_f32 v[54:55], v[34:35], v[40:41]
	v_pk_fma_f32 v[40:41], v[46:47], s[24:25], v[26:27] op_sel_hi:[1,0,0] neg_lo:[0,0,1] neg_hi:[0,0,1]
	v_pk_fma_f32 v[42:43], v[44:45], s[24:25], v[26:27] op_sel_hi:[1,0,0] neg_lo:[0,0,1] neg_hi:[0,0,1]
	v_exp_f32_e32 v46, v40
	v_exp_f32_e32 v44, v42
	v_exp_f32_e32 v45, v43
	v_exp_f32_e32 v47, v41
	v_pk_fma_f32 v[42:43], v[50:51], s[24:25], v[26:27] op_sel_hi:[1,0,0] neg_lo:[0,0,1] neg_hi:[0,0,1]
	v_pk_fma_f32 v[40:41], v[48:49], s[24:25], v[26:27] op_sel_hi:[1,0,0] neg_lo:[0,0,1] neg_hi:[0,0,1]
	v_exp_f32_e32 v42, v42
	v_exp_f32_e32 v40, v40
	v_exp_f32_e32 v41, v41
	v_exp_f32_e32 v43, v43
	v_pk_add_f32 v[48:49], v[46:47], v[54:55]
	v_pk_add_f32 v[50:51], v[44:45], v[52:53]
	v_cvt_pk_bf16_f32 v28, v28, v29
	v_pk_add_f32 v[58:59], v[42:43], v[48:49]
	v_pk_add_f32 v[56:57], v[40:41], v[50:51]
	v_pk_fma_f32 v[48:49], v[64:65], s[24:25], v[26:27] op_sel_hi:[1,0,0] neg_lo:[0,0,1] neg_hi:[0,0,1]
	v_pk_fma_f32 v[50:51], v[62:63], s[24:25], v[26:27] op_sel_hi:[1,0,0] neg_lo:[0,0,1] neg_hi:[0,0,1]
	v_exp_f32_e32 v54, v48
	v_exp_f32_e32 v52, v50
	v_exp_f32_e32 v53, v51
	v_exp_f32_e32 v55, v49
	v_pk_fma_f32 v[50:51], v[68:69], s[24:25], v[26:27] op_sel_hi:[1,0,0] neg_lo:[0,0,1] neg_hi:[0,0,1]
	v_pk_fma_f32 v[48:49], v[66:67], s[24:25], v[26:27] op_sel_hi:[1,0,0] neg_lo:[0,0,1] neg_hi:[0,0,1]
	v_exp_f32_e32 v50, v50
	v_exp_f32_e32 v48, v48
	v_exp_f32_e32 v49, v49
	v_exp_f32_e32 v51, v51
	v_pk_add_f32 v[58:59], v[54:55], v[58:59]
	v_pk_add_f32 v[56:57], v[52:53], v[56:57]
	v_pk_fma_f32 v[64:65], v[138:139], s[24:25], v[26:27] op_sel_hi:[1,0,0] neg_lo:[0,0,1] neg_hi:[0,0,1]
	v_pk_add_f32 v[60:61], v[48:49], v[56:57]
	v_pk_add_f32 v[62:63], v[50:51], v[58:59]
	v_pk_fma_f32 v[56:57], v[72:73], s[24:25], v[26:27] op_sel_hi:[1,0,0] neg_lo:[0,0,1] neg_hi:[0,0,1]
	v_pk_fma_f32 v[58:59], v[70:71], s[24:25], v[26:27] op_sel_hi:[1,0,0] neg_lo:[0,0,1] neg_hi:[0,0,1]
	v_exp_f32_e32 v70, v56
	v_exp_f32_e32 v68, v58
	v_exp_f32_e32 v69, v59
	v_exp_f32_e32 v71, v57
	v_pk_fma_f32 v[58:59], v[80:81], s[24:25], v[26:27] op_sel_hi:[1,0,0] neg_lo:[0,0,1] neg_hi:[0,0,1]
	v_exp_f32_e32 v72, v64
	v_exp_f32_e32 v58, v58
	v_exp_f32_e32 v59, v59
	v_exp_f32_e32 v73, v65
	v_pk_fma_f32 v[56:57], v[78:79], s[24:25], v[26:27] op_sel_hi:[1,0,0] neg_lo:[0,0,1] neg_hi:[0,0,1]
	v_pk_add_f32 v[62:63], v[70:71], v[62:63]
	v_exp_f32_e32 v56, v56
	v_exp_f32_e32 v57, v57
	v_pk_add_f32 v[62:63], v[58:59], v[62:63]
	v_pk_fma_f32 v[64:65], v[136:137], s[24:25], v[26:27] op_sel_hi:[1,0,0] neg_lo:[0,0,1] neg_hi:[0,0,1]
	v_pk_fma_f32 v[66:67], v[22:23], s[24:25], v[26:27] op_sel_hi:[1,0,0] neg_lo:[0,0,1] neg_hi:[0,0,1]
	v_exp_f32_e32 v74, v64
	v_exp_f32_e32 v75, v65
	v_pk_add_f32 v[64:65], v[72:73], v[62:63]
	v_pk_fma_f32 v[62:63], v[24:25], s[24:25], v[26:27] op_sel_hi:[1,0,0] neg_lo:[0,0,1] neg_hi:[0,0,1]
	v_cvt_pk_bf16_f32 v29, v30, v31
	v_cvt_pk_bf16_f32 v30, v36, v37
	v_cvt_pk_bf16_f32 v31, v38, v39
	ds_read_b128 v[36:39], v127 offset:32768
	ds_read_b128 v[22:25], v127 offset:33792
	v_exp_f32_e32 v76, v66
	v_exp_f32_e32 v77, v67
	v_exp_f32_e32 v78, v62
	v_exp_f32_e32 v79, v63
	v_pk_add_f32 v[60:61], v[68:69], v[60:61]
	v_pk_fma_f32 v[84:85], v[20:21], s[24:25], v[26:27] op_sel_hi:[1,0,0] neg_lo:[0,0,1] neg_hi:[0,0,1]
	v_pk_add_f32 v[60:61], v[56:57], v[60:61]
	v_pk_add_f32 v[82:83], v[78:79], v[64:65]
	v_pk_add_f32 v[60:61], v[74:75], v[60:61]
	ds_read_b128 v[64:67], v127 offset:35840
	v_pk_add_f32 v[80:81], v[76:77], v[60:61]
	ds_read_b128 v[60:63], v127 offset:34816
	v_cvt_pk_bf16_f32 v32, v32, v33
	v_cvt_pk_bf16_f32 v33, v34, v35
	v_cvt_pk_bf16_f32 v34, v44, v45
	v_cvt_pk_bf16_f32 v35, v46, v47
	ds_read_b128 v[44:47], v127 offset:36864
	v_pk_fma_f32 v[114:115], v[18:19], s[24:25], v[26:27] op_sel_hi:[1,0,0] neg_lo:[0,0,1] neg_hi:[0,0,1]
	ds_read_b128 v[18:21], v127 offset:37888
	s_waitcnt lgkmcnt(5)
	v_mfma_f32_16x16x32_bf16 v[36:39], v[36:39], v[28:31], 0
	v_fma_f32 v14, v14, s24, -v26
	v_fma_f32 v15, v15, s24, -v26
	s_waitcnt lgkmcnt(4)
	v_mfma_f32_16x16x32_bf16 v[22:25], v[22:25], v[28:31], 0
	s_waitcnt lgkmcnt(1)
	v_mfma_f32_16x16x32_bf16 v[36:39], v[44:47], v[32:35], v[36:39]
	ds_read_b128 v[44:47], v127 offset:38912
	s_waitcnt lgkmcnt(1)
	v_mfma_f32_16x16x32_bf16 v[18:21], v[18:21], v[32:35], v[22:25]
	s_nop 2
	ds_read_b128 v[22:25], v127 offset:39936
	v_cvt_pk_bf16_f32 v40, v40, v41
	v_cvt_pk_bf16_f32 v41, v42, v43
	v_cvt_pk_bf16_f32 v42, v52, v53
	v_cvt_pk_bf16_f32 v43, v54, v55
	ds_read_b128 v[52:55], v127 offset:40960
	v_mfma_f32_16x16x32_bf16 v[60:63], v[60:63], v[28:31], 0
	v_mfma_f32_16x16x32_bf16 v[28:31], v[64:67], v[28:31], 0
	v_exp_f32_e32 v64, v114
	v_exp_f32_e32 v66, v84
	v_exp_f32_e32 v67, v85
	s_waitcnt lgkmcnt(1)
	v_mfma_f32_16x16x32_bf16 v[22:25], v[22:25], v[32:35], v[28:31]
	v_exp_f32_e32 v65, v115
	v_pk_fma_f32 v[84:85], v[16:17], s[24:25], v[26:27] op_sel_hi:[1,0,0] neg_lo:[0,0,1] neg_hi:[0,0,1]
	v_exp_f32_e32 v114, v14
	ds_read_b128 v[28:31], v127 offset:43008
	v_mfma_f32_16x16x32_bf16 v[44:47], v[44:47], v[32:35], v[60:63]
	v_exp_f32_e32 v115, v15
	ds_read_b128 v[32:35], v127 offset:44032
	v_pk_add_f32 v[80:81], v[64:65], v[80:81]
	ds_read_b128 v[60:63], v127 offset:41984
	s_waitcnt lgkmcnt(3)
	v_mfma_f32_16x16x32_bf16 v[14:17], v[52:55], v[40:43], v[36:39]
	v_cvt_pk_bf16_f32 v36, v48, v49
	v_cvt_pk_bf16_f32 v37, v50, v51
	v_cvt_pk_bf16_f32 v38, v68, v69
	v_cvt_pk_bf16_f32 v39, v70, v71
	ds_read_b128 v[48:51], v127 offset:45056
	s_waitcnt lgkmcnt(3)
	v_mfma_f32_16x16x32_bf16 v[28:31], v[28:31], v[40:43], v[44:47]
	v_add_f32_e64 v54, v114, v80
	v_add_f32_e64 v55, v115, v81
	v_exp_f32_e32 v52, v84
	v_exp_f32_e32 v53, v85
	ds_read_b128 v[44:47], v127 offset:46080
	s_waitcnt lgkmcnt(2)
	v_mfma_f32_16x16x32_bf16 v[18:21], v[60:63], v[40:43], v[18:21]
	v_fma_f32 v62, v10, s24, -v26
	v_fma_f32 v63, v11, s24, -v26
	v_pk_add_f32 v[82:83], v[66:67], v[82:83]
	v_exp_f32_e32 v62, v62
	v_mfma_f32_16x16x32_bf16 v[22:25], v[32:35], v[40:43], v[22:25]
	v_fma_f32 v32, v12, s24, -v26
	v_fma_f32 v33, v13, s24, -v26
	v_exp_f32_e32 v63, v63
	v_pk_add_f32 v[60:61], v[52:53], v[82:83]
	s_waitcnt lgkmcnt(1)
	v_mfma_f32_16x16x32_bf16 v[10:13], v[48:51], v[36:39], v[14:17]
	v_exp_f32_e32 v48, v32
	v_exp_f32_e32 v49, v33
	ds_read_b128 v[32:35], v127 offset:48128
	ds_read_b128 v[14:17], v127 offset:47104
	s_waitcnt lgkmcnt(2)
	v_mfma_f32_16x16x32_bf16 v[18:21], v[44:47], v[36:39], v[18:21]
	v_cvt_pk_bf16_f32 v40, v56, v57
	v_cvt_pk_bf16_f32 v41, v58, v59
	v_cvt_pk_bf16_f32 v42, v74, v75
	v_cvt_pk_bf16_f32 v43, v72, v73
	ds_read_b128 v[44:47], v127 offset:49152
	s_waitcnt lgkmcnt(1)
	v_mfma_f32_16x16x32_bf16 v[14:17], v[14:17], v[36:39], v[28:31]
	v_fma_f32 v56, v8, s24, -v26
	v_fma_f32 v57, v9, s24, -v26
	s_nop 0
	ds_read_b128 v[28:31], v127 offset:50176
	v_pk_add_f32 v[54:55], v[62:63], v[54:55]
	v_mfma_f32_16x16x32_bf16 v[22:25], v[32:35], v[36:39], v[22:25]
	v_fma_f32 v32, v6, s24, -v26
	v_fma_f32 v33, v7, s24, -v26
	v_pk_add_f32 v[50:51], v[48:49], v[60:61]
	s_waitcnt lgkmcnt(1)
	v_mfma_f32_16x16x32_bf16 v[6:9], v[44:47], v[40:43], v[10:13]
	v_exp_f32_e32 v44, v32
	v_exp_f32_e32 v45, v33
	v_exp_f32_e32 v46, v56
	ds_read_b128 v[10:13], v127 offset:51200
	s_waitcnt lgkmcnt(1)
	v_mfma_f32_16x16x32_bf16 v[18:21], v[28:31], v[40:43], v[18:21]
	ds_read_b128 v[28:31], v127 offset:52224
	v_cvt_pk_bf16_f32 v32, v76, v77
	v_cvt_pk_bf16_f32 v33, v78, v79
	v_cvt_pk_bf16_f32 v34, v64, v65
	v_cvt_pk_bf16_f32 v35, v66, v67
	ds_read_b128 v[36:39], v127 offset:53248
	s_waitcnt lgkmcnt(2)
	v_mfma_f32_16x16x32_bf16 v[10:13], v[10:13], v[40:43], v[14:17]
	v_exp_f32_e32 v47, v57
	s_nop 1
	ds_read_b128 v[14:17], v127 offset:54272
	s_waitcnt lgkmcnt(2)
	v_mfma_f32_16x16x32_bf16 v[22:25], v[28:31], v[40:43], v[22:25]
	v_fma_f32 v42, v4, s24, -v26
	v_fma_f32 v43, v5, s24, -v26
	v_pk_fma_f32 v[28:29], v[2:3], s[24:25], v[26:27] op_sel_hi:[1,0,0] neg_lo:[0,0,1] neg_hi:[0,0,1]
	v_pk_add_f32 v[40:41], v[44:45], v[54:55]
	s_waitcnt lgkmcnt(1)
	v_mfma_f32_16x16x32_bf16 v[2:5], v[36:39], v[32:35], v[6:9]
	v_exp_f32_e32 v54, v28
	v_exp_f32_e32 v55, v29
	v_exp_f32_e32 v42, v42
	ds_read_b128 v[6:9], v127 offset:55296
	s_waitcnt lgkmcnt(1)
	v_mfma_f32_16x16x32_bf16 v[14:17], v[14:17], v[32:35], v[18:21]
	v_exp_f32_e32 v43, v43
	v_pk_add_f32 v[40:41], v[54:55], v[40:41]
	s_nop 0
	ds_read_b128 v[18:21], v127 offset:56320
	v_cvt_pk_bf16_f32 v28, v114, v115
	v_cvt_pk_bf16_f32 v29, v52, v53
	v_cvt_pk_bf16_f32 v30, v62, v63
	v_cvt_pk_bf16_f32 v31, v48, v49
	ds_read_b128 v[36:39], v127 offset:57344
	s_waitcnt lgkmcnt(2)
	v_mfma_f32_16x16x32_bf16 v[6:9], v[6:9], v[32:35], v[10:13]
	s_nop 2
	ds_read_b128 v[10:13], v127 offset:58368
	s_waitcnt lgkmcnt(2)
	v_mfma_f32_16x16x32_bf16 v[18:21], v[18:21], v[32:35], v[22:25]
	s_nop 2
	v_add_f32_e64 v22, v46, v50
	v_add_f32_e64 v23, v47, v51
	s_waitcnt lgkmcnt(0)
	v_mfma_f32_16x16x32_bf16 v[10:13], v[10:13], v[28:31], v[14:17]
	v_add_f32_e64 v32, v42, v22
	v_add_f32_e64 v33, v43, v23
	ds_read_b128 v[22:25], v127 offset:59392
	ds_read_b128 v[14:17], v127 offset:60416
	v_mfma_f32_16x16x32_bf16 v[2:5], v[36:39], v[28:31], v[2:5]
	v_pk_mov_b32 v[48:49], v[40:41], v[32:33] op_sel:[1,0]
	v_mov_b32_e32 v41, v33
	v_cvt_pk_bf16_f32 v32, v44, v45
	v_cvt_pk_bf16_f32 v33, v46, v47
	v_cvt_pk_bf16_f32 v34, v54, v55
	v_cvt_pk_bf16_f32 v35, v42, v43
	ds_read_b128 v[36:39], v127 offset:61440
	s_waitcnt lgkmcnt(2)
	v_mfma_f32_16x16x32_bf16 v[6:9], v[22:25], v[28:31], v[6:9]
	v_add_f32_e64 v22, v48, v40
	v_add_f32_e64 v23, v49, v41
	v_add_f32_e32 v27, v22, v23
	ds_read_b128 v[22:25], v127 offset:62464
	s_waitcnt lgkmcnt(2)
	v_mfma_f32_16x16x32_bf16 v[14:17], v[14:17], v[28:31], v[18:21]
	ds_bpermute_b32 v29, v93, v27
	v_lshlrev_b32_e32 v28, 3, v112
	s_waitcnt lgkmcnt(0)
	v_add_f32_e32 v27, v27, v29
	ds_read_b128 v[18:21], v127 offset:63488
	v_mfma_f32_16x16x32_bf16 v[2:5], v[36:39], v[32:35], v[2:5]
	ds_bpermute_b32 v36, v157, v27
	v_mov_b32_e32 v29, v89
	v_lshl_add_u64 v[30:31], s[6:7], 0, v[28:29]
	v_mfma_f32_16x16x32_bf16 v[10:13], v[22:25], v[32:35], v[10:13]
	ds_read_b128 v[22:25], v127 offset:64512
	s_waitcnt lgkmcnt(1)
	v_add_f32_e32 v27, v27, v36
	v_mfma_f32_16x16x32_bf16 v[6:9], v[18:21], v[32:35], v[6:9]
	v_div_scale_f32 v21, s[6:7], v27, v27, 1.0
	v_rcp_f32_e32 v36, v21
	s_waitcnt lgkmcnt(0)
	v_mfma_f32_16x16x32_bf16 v[14:17], v[22:25], v[32:35], v[14:17]
	v_fma_f32 v22, -v21, v36, 1.0
	v_fmac_f32_e32 v36, v22, v36
	v_div_scale_f32 v22, vcc, 1.0, v27, 1.0
	v_mul_f32_e32 v23, v22, v36
	v_fma_f32 v24, -v21, v23, v22
	v_fmac_f32_e32 v23, v24, v36
	v_fma_f32 v21, -v21, v23, v22
	v_div_fmas_f32 v21, v21, v36, v23
	v_add_u32_e32 v20, 56, v110
	v_div_fixup_f32 v21, v21, v27, 1.0
	v_lshlrev_b32_e32 v22, 2, v20
	v_mul_f32_e32 v2, v21, v2
	v_mul_f32_e32 v3, v21, v3
	v_cvt_pk_bf16_f32 v2, v2, v3
	v_mul_f32_e32 v3, v21, v4
	v_mul_f32_e32 v4, v21, v5
	v_ashrrev_i32_e32 v23, 31, v22
	v_cvt_pk_bf16_f32 v3, v3, v4
	v_lshlrev_b64 v[4:5], 9, v[22:23]
	v_lshl_add_u64 v[4:5], v[30:31], 0, v[4:5]
	global_store_dwordx2 v[4:5], v[2:3], off
	v_mul_f32_e32 v2, v21, v10
	v_mul_f32_e32 v3, v21, v11
	v_cvt_pk_bf16_f32 v2, v2, v3
	v_mul_f32_e32 v3, v21, v12
	v_mul_f32_e32 v4, v21, v13
	v_cvt_pk_bf16_f32 v3, v3, v4
	v_or_b32_e32 v4, 1, v22
	v_ashrrev_i32_e32 v5, 31, v4
	v_lshlrev_b64 v[4:5], 9, v[4:5]
	v_lshl_add_u64 v[4:5], v[30:31], 0, v[4:5]
	global_store_dwordx2 v[4:5], v[2:3], off
	v_mul_f32_e32 v2, v21, v6
	v_mul_f32_e32 v3, v21, v7
	v_cvt_pk_bf16_f32 v2, v2, v3
	v_mul_f32_e32 v3, v21, v8
	v_mul_f32_e32 v4, v21, v9
	v_cvt_pk_bf16_f32 v3, v3, v4
	v_or_b32_e32 v4, 2, v22
	v_ashrrev_i32_e32 v5, 31, v4
	v_lshlrev_b64 v[4:5], 9, v[4:5]
	v_lshl_add_u64 v[4:5], v[30:31], 0, v[4:5]
	global_store_dwordx2 v[4:5], v[2:3], off
	v_mul_f32_e32 v2, v21, v14
	v_mul_f32_e32 v3, v21, v15
	v_cvt_pk_bf16_f32 v2, v2, v3
	v_mul_f32_e32 v3, v21, v16
	v_mul_f32_e32 v4, v21, v17
	v_cvt_pk_bf16_f32 v3, v3, v4
	v_or_b32_e32 v4, 3, v22
	v_ashrrev_i32_e32 v5, 31, v4
	v_lshlrev_b64 v[4:5], 9, v[4:5]
	v_lshl_add_u64 v[4:5], v[30:31], 0, v[4:5]
	v_ashrrev_i32_e32 v21, 31, v20
	v_lshl_add_u64 v[18:19], s[4:5], 0, v[28:29]
	global_store_dwordx2 v[4:5], v[2:3], off
	v_lshlrev_b64 v[2:3], 9, v[20:21]
	v_lshl_add_u64 v[2:3], v[18:19], 0, v[2:3]
	v_cmp_gt_i32_e32 vcc, s76, v94
	global_store_dwordx2 v[2:3], v[26:27], off
	s_barrier
	s_and_saveexec_b64 s[4:5], vcc
	s_cbranch_execz .LBB0_670
	s_mulk_i32 s10, 0x1d1
	v_add_u32_e32 v2, s10, v94
	v_ashrrev_i32_e32 v3, 31, v2
	v_lshl_add_u64 v[2:3], v[2:3], 2, s[12:13]
	global_load_dword v2, v[2:3], off
	v_lshl_add_u32 v3, v94, 2, 0
	v_add_u32_e32 v3, 0x24000, v3
	s_waitcnt vmcnt(0)
	v_mul_f32_e32 v2, 0x3fb8aa3b, v2
	ds_write_b32 v3, v2
